# all validated work reductions together: v15 + header shift-math, relaxed waits only in peeled iterations, counted QK waits, attention drain removal, nt final stores, shorter hand-over, alignment barri
# speedup vs baseline: 1.0175x; 1.0124x over previous
.Lpl1_join_1:
	s_waitcnt lgkmcnt(0)
	s_setprio 1
	s_barrier
	v_mfma_f32_16x16x32_bf16 v[130:133], v[134:137], v[186:189], 0
	v_mfma_f32_16x16x32_bf16 v[130:133], v[150:153], v[202:205], v[130:133]
	v_mfma_f32_16x16x32_bf16 v[126:129], v[154:157], v[186:189], 0
	v_mfma_f32_16x16x32_bf16 v[126:129], v[158:161], v[202:205], v[126:129]
	v_mfma_f32_16x16x32_bf16 v[114:117], v[134:137], v[206:209], 0
	v_mfma_f32_16x16x32_bf16 v[114:117], v[150:153], v[210:213], v[114:117]
	v_mfma_f32_16x16x32_bf16 v[110:113], v[154:157], v[206:209], 0
	v_mfma_f32_16x16x32_bf16 v[110:113], v[158:161], v[210:213], v[110:113]
	v_mfma_f32_16x16x32_bf16 v[98:101], v[134:137], v[214:217], 0
	v_mfma_f32_16x16x32_bf16 v[98:101], v[150:153], v[218:221], v[98:101]
	v_mfma_f32_16x16x32_bf16 v[94:97], v[154:157], v[214:217], 0
	v_mfma_f32_16x16x32_bf16 v[94:97], v[158:161], v[218:221], v[94:97]
	v_mfma_f32_16x16x32_bf16 v[82:85], v[134:137], v[222:225], 0
	v_mfma_f32_16x16x32_bf16 v[82:85], v[150:153], v[226:229], v[82:85]
	v_mfma_f32_16x16x32_bf16 v[78:81], v[154:157], v[222:225], 0
	v_mfma_f32_16x16x32_bf16 v[78:81], v[158:161], v[226:229], v[78:81]
	v_mfma_f32_16x16x32_bf16 v[122:125], v[162:165], v[186:189], 0
	v_mfma_f32_16x16x32_bf16 v[122:125], v[166:169], v[202:205], v[122:125]
	v_mfma_f32_16x16x32_bf16 v[118:121], v[170:173], v[186:189], 0
	v_mfma_f32_16x16x32_bf16 v[118:121], v[182:185], v[202:205], v[118:121]
	v_mfma_f32_16x16x32_bf16 v[106:109], v[162:165], v[206:209], 0
	v_mfma_f32_16x16x32_bf16 v[106:109], v[166:169], v[210:213], v[106:109]
	v_mfma_f32_16x16x32_bf16 v[102:105], v[170:173], v[206:209], 0
	v_mfma_f32_16x16x32_bf16 v[102:105], v[182:185], v[210:213], v[102:105]
	v_mfma_f32_16x16x32_bf16 v[90:93], v[162:165], v[214:217], 0
	v_mfma_f32_16x16x32_bf16 v[90:93], v[166:169], v[218:221], v[90:93]
	v_mfma_f32_16x16x32_bf16 v[86:89], v[170:173], v[214:217], 0
	v_mfma_f32_16x16x32_bf16 v[86:89], v[182:185], v[218:221], v[86:89]
	v_mfma_f32_16x16x32_bf16 v[74:77], v[162:165], v[222:225], 0
	v_mfma_f32_16x16x32_bf16 v[74:77], v[166:169], v[226:229], v[74:77]
	v_mfma_f32_16x16x32_bf16 v[70:73], v[170:173], v[222:225], 0
	v_mfma_f32_16x16x32_bf16 v[70:73], v[182:185], v[226:229], v[70:73]
	s_barrier
	s_setprio 0
	s_add_i32 s52, s52, s36
	v_lshl_add_u64 v[174:175], s[30:31], 0, v[0:1]
	s_mov_b32 m0, s52
	ds_read_b128 v[186:189], v201 offset:16384
	ds_read_b128 v[202:205], v201 offset:17408
	ds_read_b128 v[206:209], v201 offset:18432
	ds_read_b128 v[210:213], v201 offset:19456
	ds_read_b128 v[214:217], v201 offset:20480
	ds_read_b128 v[218:221], v201 offset:21504
	ds_read_b128 v[222:225], v201 offset:22528
	ds_read_b128 v[226:229], v201 offset:23552
	global_load_lds_dwordx4 v[174:175], off
	s_add_i32 m0, s52, 0x2000
	s_add_u32 s52, s30, 0x40000
	v_lshl_add_u64 v[190:191], s[30:31], 0, v[14:15]
	s_addc_u32 s53, s31, 0
	s_add_i32 s54, s54, s36
	global_load_lds_dwordx4 v[190:191], off
	v_lshl_add_u64 v[230:231], s[52:53], 0, v[0:1]
	s_mov_b32 m0, s54
	v_lshl_add_u64 v[232:233], s[34:35], 0, v[138:139]
	global_load_lds_dwordx4 v[230:231], off
	v_lshl_add_u64 v[230:231], s[52:53], 0, v[14:15]
	s_add_i32 m0, s54, 0x2000
	s_nop 0
	global_load_lds_dwordx4 v[230:231], off
	v_lshl_add_u64 v[230:231], s[34:35], 0, v[140:141]
	s_mov_b32 m0, s39
	s_nop 0
	global_load_lds_dwordx4 v[230:231], off
	s_mov_b32 m0, s40
	s_nop 0
	global_load_lds_dwordx4 v[232:233], off
	s_cmp_lg_u32 s2, 0
	s_cbranch_scc1 .Lpl1_relax_2
	s_waitcnt vmcnt(8)
	s_branch .Lpl1_join_2

.Lpl1_join_2:
	s_waitcnt lgkmcnt(0)
	s_setprio 1
	s_barrier
	v_mfma_f32_16x16x32_bf16 v[66:69], v[134:137], v[186:189], 0
	v_mfma_f32_16x16x32_bf16 v[66:69], v[150:153], v[202:205], v[66:69]
	v_mfma_f32_16x16x32_bf16 v[62:65], v[154:157], v[186:189], 0
	v_mfma_f32_16x16x32_bf16 v[62:65], v[158:161], v[202:205], v[62:65]
	v_mfma_f32_16x16x32_bf16 v[50:53], v[134:137], v[206:209], 0
	v_mfma_f32_16x16x32_bf16 v[50:53], v[150:153], v[210:213], v[50:53]
	v_mfma_f32_16x16x32_bf16 v[46:49], v[154:157], v[206:209], 0
	v_mfma_f32_16x16x32_bf16 v[46:49], v[158:161], v[210:213], v[46:49]
	v_mfma_f32_16x16x32_bf16 v[34:37], v[134:137], v[214:217], 0
	v_mfma_f32_16x16x32_bf16 v[34:37], v[150:153], v[218:221], v[34:37]
	v_mfma_f32_16x16x32_bf16 v[30:33], v[154:157], v[214:217], 0
	v_mfma_f32_16x16x32_bf16 v[30:33], v[158:161], v[218:221], v[30:33]
	v_mfma_f32_16x16x32_bf16 v[18:21], v[134:137], v[222:225], 0
	v_mfma_f32_16x16x32_bf16 v[18:21], v[150:153], v[226:229], v[18:21]
	v_mfma_f32_16x16x32_bf16 v[10:13], v[154:157], v[222:225], 0
	v_mfma_f32_16x16x32_bf16 v[10:13], v[158:161], v[226:229], v[10:13]
	v_mfma_f32_16x16x32_bf16 v[58:61], v[162:165], v[186:189], 0
	v_mfma_f32_16x16x32_bf16 v[58:61], v[166:169], v[202:205], v[58:61]
	v_mfma_f32_16x16x32_bf16 v[54:57], v[170:173], v[186:189], 0
	v_mfma_f32_16x16x32_bf16 v[54:57], v[182:185], v[202:205], v[54:57]
	v_mfma_f32_16x16x32_bf16 v[42:45], v[162:165], v[206:209], 0
	v_mfma_f32_16x16x32_bf16 v[42:45], v[166:169], v[210:213], v[42:45]
	v_mfma_f32_16x16x32_bf16 v[38:41], v[170:173], v[206:209], 0
	v_mfma_f32_16x16x32_bf16 v[38:41], v[182:185], v[210:213], v[38:41]
	v_mfma_f32_16x16x32_bf16 v[26:29], v[162:165], v[214:217], 0
	v_mfma_f32_16x16x32_bf16 v[26:29], v[166:169], v[218:221], v[26:29]
	v_mfma_f32_16x16x32_bf16 v[22:25], v[170:173], v[214:217], 0
	v_mfma_f32_16x16x32_bf16 v[22:25], v[182:185], v[218:221], v[22:25]
	v_mfma_f32_16x16x32_bf16 v[6:9], v[162:165], v[222:225], 0
	v_mfma_f32_16x16x32_bf16 v[6:9], v[166:169], v[226:229], v[6:9]
	v_mfma_f32_16x16x32_bf16 v[2:5], v[170:173], v[222:225], 0
	v_mfma_f32_16x16x32_bf16 v[2:5], v[182:185], v[226:229], v[2:5]
	s_barrier
	s_setprio 0
	s_add_i32 s52, 0, 0x18000
	s_add_i32 s53, 0, 0x1c000
	v_add_u32_e32 v158, s52, v199
	v_add_u32_e32 v182, s53, v199
	ds_read_b128 v[134:137], v158
	ds_read_b128 v[150:153], v158 offset:1024
	ds_read_b128 v[154:157], v158 offset:2048
	ds_read_b128 v[158:161], v158 offset:3072
	ds_read_b128 v[162:165], v182
	ds_read_b128 v[166:169], v182 offset:1024
	ds_read_b128 v[170:173], v182 offset:2048
	ds_read_b128 v[182:185], v182 offset:3072
	s_add_u32 s34, s34, 0x40000
	s_addc_u32 s35, s35, 0
	s_mov_b32 m0, s41
	v_lshl_add_u64 v[234:235], s[34:35], 0, v[140:141]
	ds_read_b128 v[186:189], v201 offset:32768
	ds_read_b128 v[202:205], v201 offset:33792
	ds_read_b128 v[206:209], v201 offset:34816
	ds_read_b128 v[210:213], v201 offset:35840
	ds_read_b128 v[214:217], v201 offset:36864
	ds_read_b128 v[218:221], v201 offset:37888
	ds_read_b128 v[222:225], v201 offset:38912
	ds_read_b128 v[226:229], v201 offset:39936
	global_load_lds_dwordx4 v[234:235], off
	v_lshl_add_u64 v[234:235], s[34:35], 0, v[138:139]
	s_mov_b32 m0, s42
	s_nop 0
	global_load_lds_dwordx4 v[234:235], off
	s_waitcnt vmcnt(8)
	s_waitcnt lgkmcnt(0)
	s_setprio 1
	s_barrier
	v_mfma_f32_16x16x32_bf16 v[130:133], v[134:137], v[186:189], v[130:133]
	v_mfma_f32_16x16x32_bf16 v[130:133], v[150:153], v[202:205], v[130:133]
	v_mfma_f32_16x16x32_bf16 v[126:129], v[154:157], v[186:189], v[126:129]
	v_mfma_f32_16x16x32_bf16 v[126:129], v[158:161], v[202:205], v[126:129]
	v_mfma_f32_16x16x32_bf16 v[114:117], v[134:137], v[206:209], v[114:117]
	v_mfma_f32_16x16x32_bf16 v[114:117], v[150:153], v[210:213], v[114:117]
	v_mfma_f32_16x16x32_bf16 v[110:113], v[154:157], v[206:209], v[110:113]
	v_mfma_f32_16x16x32_bf16 v[110:113], v[158:161], v[210:213], v[110:113]
	v_mfma_f32_16x16x32_bf16 v[98:101], v[134:137], v[214:217], v[98:101]
	v_mfma_f32_16x16x32_bf16 v[98:101], v[150:153], v[218:221], v[98:101]
	v_mfma_f32_16x16x32_bf16 v[94:97], v[154:157], v[214:217], v[94:97]
	v_mfma_f32_16x16x32_bf16 v[94:97], v[158:161], v[218:221], v[94:97]
	v_mfma_f32_16x16x32_bf16 v[82:85], v[134:137], v[222:225], v[82:85]
	v_mfma_f32_16x16x32_bf16 v[82:85], v[150:153], v[226:229], v[82:85]
	v_mfma_f32_16x16x32_bf16 v[78:81], v[154:157], v[222:225], v[78:81]
	v_mfma_f32_16x16x32_bf16 v[78:81], v[158:161], v[226:229], v[78:81]
	v_mfma_f32_16x16x32_bf16 v[122:125], v[162:165], v[186:189], v[122:125]
	v_mfma_f32_16x16x32_bf16 v[122:125], v[166:169], v[202:205], v[122:125]
	v_mfma_f32_16x16x32_bf16 v[118:121], v[170:173], v[186:189], v[118:121]
	v_mfma_f32_16x16x32_bf16 v[118:121], v[182:185], v[202:205], v[118:121]
	v_mfma_f32_16x16x32_bf16 v[106:109], v[162:165], v[206:209], v[106:109]
	v_mfma_f32_16x16x32_bf16 v[106:109], v[166:169], v[210:213], v[106:109]
	v_mfma_f32_16x16x32_bf16 v[102:105], v[170:173], v[206:209], v[102:105]
	v_mfma_f32_16x16x32_bf16 v[102:105], v[182:185], v[210:213], v[102:105]
	v_mfma_f32_16x16x32_bf16 v[90:93], v[162:165], v[214:217], v[90:93]
	v_mfma_f32_16x16x32_bf16 v[90:93], v[166:169], v[218:221], v[90:93]
	v_mfma_f32_16x16x32_bf16 v[86:89], v[170:173], v[214:217], v[86:89]
	v_mfma_f32_16x16x32_bf16 v[86:89], v[182:185], v[218:221], v[86:89]
	v_mfma_f32_16x16x32_bf16 v[74:77], v[162:165], v[222:225], v[74:77]
	v_mfma_f32_16x16x32_bf16 v[74:77], v[166:169], v[226:229], v[74:77]
	v_mfma_f32_16x16x32_bf16 v[70:73], v[170:173], v[222:225], v[70:73]
	v_mfma_f32_16x16x32_bf16 v[70:73], v[182:185], v[226:229], v[70:73]
	s_barrier
	s_setprio 0
	s_add_i32 s34, s52, s36
	v_lshl_add_u64 v[174:175], v[174:175], 0, s[92:93]
	s_mov_b32 m0, s34
	ds_read_b128 v[186:189], v201 offset:49152
	ds_read_b128 v[202:205], v201 offset:50176
	ds_read_b128 v[206:209], v201 offset:51200
	ds_read_b128 v[210:213], v201 offset:52224
	ds_read_b128 v[214:217], v201 offset:53248
	ds_read_b128 v[218:221], v201 offset:54272
	ds_read_b128 v[222:225], v201 offset:55296
	ds_read_b128 v[226:229], v201 offset:56320
	global_load_lds_dwordx4 v[174:175], off
	s_add_i32 m0, s34, 0x2000
	s_add_u32 s30, s30, 0x40080
	v_lshl_add_u64 v[174:175], v[190:191], 0, s[92:93]
	s_addc_u32 s31, s31, 0
	s_add_i32 s34, s53, s36
	global_load_lds_dwordx4 v[174:175], off
	v_lshl_add_u64 v[174:175], s[30:31], 0, v[0:1]
	s_mov_b32 m0, s34
	s_nop 0
	global_load_lds_dwordx4 v[174:175], off
	v_lshl_add_u64 v[174:175], s[30:31], 0, v[14:15]
	s_add_i32 m0, s34, 0x2000
	s_nop 0
	global_load_lds_dwordx4 v[174:175], off
	v_lshl_add_u64 v[174:175], v[230:231], 0, s[92:93]
	s_mov_b32 m0, s43
	s_nop 0
	global_load_lds_dwordx4 v[174:175], off
	v_lshl_add_u64 v[174:175], v[232:233], 0, s[92:93]
	s_mov_b32 m0, s44
	s_nop 0
	global_load_lds_dwordx4 v[174:175], off
	s_waitcnt vmcnt(8)
	s_waitcnt lgkmcnt(0)
	s_setprio 1
	s_barrier
	v_mfma_f32_16x16x32_bf16 v[66:69], v[134:137], v[186:189], v[66:69]
	v_mfma_f32_16x16x32_bf16 v[66:69], v[150:153], v[202:205], v[66:69]
	v_mfma_f32_16x16x32_bf16 v[62:65], v[154:157], v[186:189], v[62:65]
	v_mfma_f32_16x16x32_bf16 v[62:65], v[158:161], v[202:205], v[62:65]
	v_mfma_f32_16x16x32_bf16 v[50:53], v[134:137], v[206:209], v[50:53]
	v_mfma_f32_16x16x32_bf16 v[50:53], v[150:153], v[210:213], v[50:53]
	v_mfma_f32_16x16x32_bf16 v[46:49], v[154:157], v[206:209], v[46:49]
	v_mfma_f32_16x16x32_bf16 v[46:49], v[158:161], v[210:213], v[46:49]
	v_mfma_f32_16x16x32_bf16 v[34:37], v[134:137], v[214:217], v[34:37]
	v_mfma_f32_16x16x32_bf16 v[34:37], v[150:153], v[218:221], v[34:37]
	v_mfma_f32_16x16x32_bf16 v[30:33], v[154:157], v[214:217], v[30:33]
	v_mfma_f32_16x16x32_bf16 v[30:33], v[158:161], v[218:221], v[30:33]
	v_mfma_f32_16x16x32_bf16 v[18:21], v[134:137], v[222:225], v[18:21]
	v_mfma_f32_16x16x32_bf16 v[18:21], v[150:153], v[226:229], v[18:21]
	v_mfma_f32_16x16x32_bf16 v[10:13], v[154:157], v[222:225], v[10:13]
	v_mfma_f32_16x16x32_bf16 v[10:13], v[158:161], v[226:229], v[10:13]
	v_mfma_f32_16x16x32_bf16 v[58:61], v[162:165], v[186:189], v[58:61]
	v_mfma_f32_16x16x32_bf16 v[58:61], v[166:169], v[202:205], v[58:61]
	v_mfma_f32_16x16x32_bf16 v[54:57], v[170:173], v[186:189], v[54:57]
	v_mfma_f32_16x16x32_bf16 v[54:57], v[182:185], v[202:205], v[54:57]
	v_mfma_f32_16x16x32_bf16 v[42:45], v[162:165], v[206:209], v[42:45]
	v_mfma_f32_16x16x32_bf16 v[42:45], v[166:169], v[210:213], v[42:45]
	v_mfma_f32_16x16x32_bf16 v[38:41], v[170:173], v[206:209], v[38:41]
	v_mfma_f32_16x16x32_bf16 v[38:41], v[182:185], v[210:213], v[38:41]
	v_mfma_f32_16x16x32_bf16 v[26:29], v[162:165], v[214:217], v[26:29]
	v_mfma_f32_16x16x32_bf16 v[26:29], v[166:169], v[218:221], v[26:29]
	v_mfma_f32_16x16x32_bf16 v[22:25], v[170:173], v[214:217], v[22:25]
	v_mfma_f32_16x16x32_bf16 v[22:25], v[182:185], v[218:221], v[22:25]
	v_mfma_f32_16x16x32_bf16 v[6:9], v[162:165], v[222:225], v[6:9]
	v_mfma_f32_16x16x32_bf16 v[6:9], v[166:169], v[226:229], v[6:9]
	v_mfma_f32_16x16x32_bf16 v[2:5], v[170:173], v[222:225], v[2:5]
	v_mfma_f32_16x16x32_bf16 v[2:5], v[182:185], v[226:229], v[2:5]
	s_barrier
	s_setprio 0
	s_add_i32 s51, s51, 2
	s_add_u32 s0, s0, 0x100
	s_addc_u32 s1, s1, 0
	s_add_u32 s49, s49, 0x100
	s_addc_u32 s50, s50, 0
	s_cmp_gt_u32 s51, 13
	s_cbranch_scc1 .Lpeel_exit_1

.Lpl2_join_1:
	s_waitcnt lgkmcnt(0)
	s_setprio 1
	s_barrier
	v_mfma_f32_16x16x32_bf16 v[130:133], v[142:145], v[182:185], 0
	v_mfma_f32_16x16x32_bf16 v[130:133], v[146:149], v[186:189], v[130:133]
	v_mfma_f32_16x16x32_bf16 v[126:129], v[150:153], v[182:185], 0
	v_mfma_f32_16x16x32_bf16 v[126:129], v[154:157], v[186:189], v[126:129]
	v_mfma_f32_16x16x32_bf16 v[114:117], v[142:145], v[190:193], 0
	v_mfma_f32_16x16x32_bf16 v[114:117], v[146:149], v[194:197], v[114:117]
	v_mfma_f32_16x16x32_bf16 v[110:113], v[150:153], v[190:193], 0
	v_mfma_f32_16x16x32_bf16 v[110:113], v[154:157], v[194:197], v[110:113]
	v_mfma_f32_16x16x32_bf16 v[98:101], v[142:145], v[198:201], 0
	v_mfma_f32_16x16x32_bf16 v[98:101], v[146:149], v[202:205], v[98:101]
	v_mfma_f32_16x16x32_bf16 v[94:97], v[150:153], v[198:201], 0
	v_mfma_f32_16x16x32_bf16 v[94:97], v[154:157], v[202:205], v[94:97]
	v_mfma_f32_16x16x32_bf16 v[82:85], v[142:145], v[206:209], 0
	v_mfma_f32_16x16x32_bf16 v[82:85], v[146:149], v[210:213], v[82:85]
	v_mfma_f32_16x16x32_bf16 v[78:81], v[150:153], v[206:209], 0
	v_mfma_f32_16x16x32_bf16 v[78:81], v[154:157], v[210:213], v[78:81]
	v_mfma_f32_16x16x32_bf16 v[122:125], v[158:161], v[182:185], 0
	v_mfma_f32_16x16x32_bf16 v[122:125], v[162:165], v[186:189], v[122:125]
	v_mfma_f32_16x16x32_bf16 v[118:121], v[166:169], v[182:185], 0
	v_mfma_f32_16x16x32_bf16 v[118:121], v[170:173], v[186:189], v[118:121]
	v_mfma_f32_16x16x32_bf16 v[106:109], v[158:161], v[190:193], 0
	v_mfma_f32_16x16x32_bf16 v[106:109], v[162:165], v[194:197], v[106:109]
	v_mfma_f32_16x16x32_bf16 v[102:105], v[166:169], v[190:193], 0
	v_mfma_f32_16x16x32_bf16 v[102:105], v[170:173], v[194:197], v[102:105]
	v_mfma_f32_16x16x32_bf16 v[90:93], v[158:161], v[198:201], 0
	v_mfma_f32_16x16x32_bf16 v[90:93], v[162:165], v[202:205], v[90:93]
	v_mfma_f32_16x16x32_bf16 v[86:89], v[166:169], v[198:201], 0
	v_mfma_f32_16x16x32_bf16 v[86:89], v[170:173], v[202:205], v[86:89]
	v_mfma_f32_16x16x32_bf16 v[74:77], v[158:161], v[206:209], 0
	v_mfma_f32_16x16x32_bf16 v[74:77], v[162:165], v[210:213], v[74:77]
	v_mfma_f32_16x16x32_bf16 v[70:73], v[166:169], v[206:209], 0
	v_mfma_f32_16x16x32_bf16 v[70:73], v[170:173], v[210:213], v[70:73]
	s_barrier
	s_setprio 0
	s_add_i32 s50, s50, s30
	v_lshl_add_u64 v[174:175], s[48:49], 0, v[0:1]
	s_mov_b32 m0, s50
	ds_read_b128 v[182:185], v251 offset:16384
	ds_read_b128 v[186:189], v251 offset:17408
	ds_read_b128 v[190:193], v251 offset:18432
	ds_read_b128 v[194:197], v251 offset:19456
	ds_read_b128 v[198:201], v251 offset:20480
	ds_read_b128 v[202:205], v251 offset:21504
	ds_read_b128 v[206:209], v251 offset:22528
	ds_read_b128 v[210:213], v251 offset:23552
	global_load_lds_dwordx4 v[174:175], off
	s_add_i32 m0, s50, 0x2000
	v_lshl_add_u64 v[214:215], s[48:49], 0, v[14:15]
	s_add_u32 s48, s48, s10
	s_addc_u32 s49, s49, 0
	s_add_i32 s50, s51, s30
	global_load_lds_dwordx4 v[214:215], off
	v_lshl_add_u64 v[216:217], s[48:49], 0, v[0:1]
	s_mov_b32 m0, s50
	v_lshl_add_u64 v[218:219], s[48:49], 0, v[14:15]
	global_load_lds_dwordx4 v[216:217], off
	s_add_i32 m0, s50, 0x2000
	v_lshl_add_u64 v[220:221], s[24:25], 0, v[0:1]
	global_load_lds_dwordx4 v[218:219], off
	s_mov_b32 m0, s31
	v_lshl_add_u64 v[222:223], s[24:25], 0, v[14:15]
	global_load_lds_dwordx4 v[220:221], off
	s_mov_b32 m0, s34
	s_nop 0
	global_load_lds_dwordx4 v[222:223], off
	s_cmp_gt_u32 s41, 1
	s_cbranch_scc1 .Lpl2_relax_2
	s_waitcnt vmcnt(8)
	s_branch .Lpl2_join_2

.Lpl2_join_2:
	s_waitcnt lgkmcnt(0)
	s_setprio 1
	s_barrier
	v_mfma_f32_16x16x32_bf16 v[66:69], v[142:145], v[182:185], 0
	v_mfma_f32_16x16x32_bf16 v[66:69], v[146:149], v[186:189], v[66:69]
	v_mfma_f32_16x16x32_bf16 v[62:65], v[150:153], v[182:185], 0
	v_mfma_f32_16x16x32_bf16 v[62:65], v[154:157], v[186:189], v[62:65]
	v_mfma_f32_16x16x32_bf16 v[50:53], v[142:145], v[190:193], 0
	v_mfma_f32_16x16x32_bf16 v[50:53], v[146:149], v[194:197], v[50:53]
	v_mfma_f32_16x16x32_bf16 v[46:49], v[150:153], v[190:193], 0
	v_mfma_f32_16x16x32_bf16 v[46:49], v[154:157], v[194:197], v[46:49]
	v_mfma_f32_16x16x32_bf16 v[34:37], v[142:145], v[198:201], 0
	v_mfma_f32_16x16x32_bf16 v[34:37], v[146:149], v[202:205], v[34:37]
	v_mfma_f32_16x16x32_bf16 v[30:33], v[150:153], v[198:201], 0
	v_mfma_f32_16x16x32_bf16 v[30:33], v[154:157], v[202:205], v[30:33]
	v_mfma_f32_16x16x32_bf16 v[18:21], v[142:145], v[206:209], 0
	v_mfma_f32_16x16x32_bf16 v[18:21], v[146:149], v[210:213], v[18:21]
	v_mfma_f32_16x16x32_bf16 v[10:13], v[150:153], v[206:209], 0
	v_mfma_f32_16x16x32_bf16 v[10:13], v[154:157], v[210:213], v[10:13]
	v_mfma_f32_16x16x32_bf16 v[58:61], v[158:161], v[182:185], 0
	v_mfma_f32_16x16x32_bf16 v[58:61], v[162:165], v[186:189], v[58:61]
	v_mfma_f32_16x16x32_bf16 v[54:57], v[166:169], v[182:185], 0
	v_mfma_f32_16x16x32_bf16 v[54:57], v[170:173], v[186:189], v[54:57]
	v_mfma_f32_16x16x32_bf16 v[42:45], v[158:161], v[190:193], 0
	v_mfma_f32_16x16x32_bf16 v[42:45], v[162:165], v[194:197], v[42:45]
	v_mfma_f32_16x16x32_bf16 v[38:41], v[166:169], v[190:193], 0
	v_mfma_f32_16x16x32_bf16 v[38:41], v[170:173], v[194:197], v[38:41]
	v_mfma_f32_16x16x32_bf16 v[26:29], v[158:161], v[198:201], 0
	v_mfma_f32_16x16x32_bf16 v[26:29], v[162:165], v[202:205], v[26:29]
	v_mfma_f32_16x16x32_bf16 v[22:25], v[166:169], v[198:201], 0
	v_mfma_f32_16x16x32_bf16 v[22:25], v[170:173], v[202:205], v[22:25]
	v_mfma_f32_16x16x32_bf16 v[6:9], v[158:161], v[206:209], 0
	v_mfma_f32_16x16x32_bf16 v[6:9], v[162:165], v[210:213], v[6:9]
	v_mfma_f32_16x16x32_bf16 v[2:5], v[166:169], v[206:209], 0
	v_mfma_f32_16x16x32_bf16 v[2:5], v[170:173], v[210:213], v[2:5]
	s_barrier
	s_setprio 0
	s_add_i32 s48, 0, 0x18000
	v_add_u32_e32 v135, s48, v249
	s_add_i32 s49, 0, 0x1c000
	ds_read_b128 v[142:145], v135
	ds_read_b128 v[146:149], v135 offset:1024
	ds_read_b128 v[150:153], v135 offset:2048
	ds_read_b128 v[154:157], v135 offset:3072
	v_add_u32_e32 v135, s49, v249
	ds_read_b128 v[158:161], v135
	ds_read_b128 v[162:165], v135 offset:1024
	ds_read_b128 v[166:169], v135 offset:2048
	ds_read_b128 v[170:173], v135 offset:3072
	s_add_u32 s24, s24, s10
	s_addc_u32 s25, s25, 0
	s_mov_b32 m0, s35
	v_lshl_add_u64 v[224:225], s[24:25], 0, v[0:1]
	ds_read_b128 v[182:185], v251 offset:32768
	ds_read_b128 v[186:189], v251 offset:33792
	ds_read_b128 v[190:193], v251 offset:34816
	ds_read_b128 v[194:197], v251 offset:35840
	ds_read_b128 v[198:201], v251 offset:36864
	ds_read_b128 v[202:205], v251 offset:37888
	ds_read_b128 v[206:209], v251 offset:38912
	ds_read_b128 v[210:213], v251 offset:39936
	global_load_lds_dwordx4 v[224:225], off
	v_lshl_add_u64 v[224:225], s[24:25], 0, v[14:15]
	s_mov_b32 m0, s36
	s_nop 0
	global_load_lds_dwordx4 v[224:225], off
	s_waitcnt vmcnt(8)
	s_waitcnt lgkmcnt(0)
	s_setprio 1
	s_barrier
	v_mfma_f32_16x16x32_bf16 v[130:133], v[142:145], v[182:185], v[130:133]
	v_mfma_f32_16x16x32_bf16 v[130:133], v[146:149], v[186:189], v[130:133]
	v_mfma_f32_16x16x32_bf16 v[126:129], v[150:153], v[182:185], v[126:129]
	v_mfma_f32_16x16x32_bf16 v[126:129], v[154:157], v[186:189], v[126:129]
	v_mfma_f32_16x16x32_bf16 v[114:117], v[142:145], v[190:193], v[114:117]
	v_mfma_f32_16x16x32_bf16 v[114:117], v[146:149], v[194:197], v[114:117]
	v_mfma_f32_16x16x32_bf16 v[110:113], v[150:153], v[190:193], v[110:113]
	v_mfma_f32_16x16x32_bf16 v[110:113], v[154:157], v[194:197], v[110:113]
	v_mfma_f32_16x16x32_bf16 v[98:101], v[142:145], v[198:201], v[98:101]
	v_mfma_f32_16x16x32_bf16 v[98:101], v[146:149], v[202:205], v[98:101]
	v_mfma_f32_16x16x32_bf16 v[94:97], v[150:153], v[198:201], v[94:97]
	v_mfma_f32_16x16x32_bf16 v[94:97], v[154:157], v[202:205], v[94:97]
	v_mfma_f32_16x16x32_bf16 v[82:85], v[142:145], v[206:209], v[82:85]
	v_mfma_f32_16x16x32_bf16 v[82:85], v[146:149], v[210:213], v[82:85]
	v_mfma_f32_16x16x32_bf16 v[78:81], v[150:153], v[206:209], v[78:81]
	v_mfma_f32_16x16x32_bf16 v[78:81], v[154:157], v[210:213], v[78:81]
	v_mfma_f32_16x16x32_bf16 v[122:125], v[158:161], v[182:185], v[122:125]
	v_mfma_f32_16x16x32_bf16 v[122:125], v[162:165], v[186:189], v[122:125]
	v_mfma_f32_16x16x32_bf16 v[118:121], v[166:169], v[182:185], v[118:121]
	v_mfma_f32_16x16x32_bf16 v[118:121], v[170:173], v[186:189], v[118:121]
	v_mfma_f32_16x16x32_bf16 v[106:109], v[158:161], v[190:193], v[106:109]
	v_mfma_f32_16x16x32_bf16 v[106:109], v[162:165], v[194:197], v[106:109]
	v_mfma_f32_16x16x32_bf16 v[102:105], v[166:169], v[190:193], v[102:105]
	v_mfma_f32_16x16x32_bf16 v[102:105], v[170:173], v[194:197], v[102:105]
	v_mfma_f32_16x16x32_bf16 v[90:93], v[158:161], v[198:201], v[90:93]
	v_mfma_f32_16x16x32_bf16 v[90:93], v[162:165], v[202:205], v[90:93]
	v_mfma_f32_16x16x32_bf16 v[86:89], v[166:169], v[198:201], v[86:89]
	v_mfma_f32_16x16x32_bf16 v[86:89], v[170:173], v[202:205], v[86:89]
	v_mfma_f32_16x16x32_bf16 v[74:77], v[158:161], v[206:209], v[74:77]
	v_mfma_f32_16x16x32_bf16 v[74:77], v[162:165], v[210:213], v[74:77]
	v_mfma_f32_16x16x32_bf16 v[70:73], v[166:169], v[206:209], v[70:73]
	v_mfma_f32_16x16x32_bf16 v[70:73], v[170:173], v[210:213], v[70:73]
	s_barrier
	s_setprio 0
	s_add_i32 s24, s48, s30
	v_lshl_add_u64 v[174:175], v[174:175], 0, s[92:93]
	s_mov_b32 m0, s24
	ds_read_b128 v[182:185], v251 offset:49152
	ds_read_b128 v[186:189], v251 offset:50176
	ds_read_b128 v[190:193], v251 offset:51200
	ds_read_b128 v[194:197], v251 offset:52224
	ds_read_b128 v[198:201], v251 offset:53248
	ds_read_b128 v[202:205], v251 offset:54272
	ds_read_b128 v[206:209], v251 offset:55296
	ds_read_b128 v[210:213], v251 offset:56320
	global_load_lds_dwordx4 v[174:175], off
	v_lshl_add_u64 v[174:175], v[214:215], 0, s[92:93]
	s_add_i32 m0, s24, 0x2000
	s_add_i32 s24, s49, s30
	global_load_lds_dwordx4 v[174:175], off
	v_lshl_add_u64 v[174:175], v[216:217], 0, s[92:93]
	s_mov_b32 m0, s24
	s_nop 0
	global_load_lds_dwordx4 v[174:175], off
	v_lshl_add_u64 v[174:175], v[218:219], 0, s[92:93]
	s_add_i32 m0, s24, 0x2000
	s_nop 0
	global_load_lds_dwordx4 v[174:175], off
	v_lshl_add_u64 v[174:175], v[220:221], 0, s[92:93]
	s_mov_b32 m0, s37
	s_nop 0
	global_load_lds_dwordx4 v[174:175], off
	v_lshl_add_u64 v[174:175], v[222:223], 0, s[92:93]
	s_mov_b32 m0, s38
	s_nop 0
	global_load_lds_dwordx4 v[174:175], off
	s_waitcnt vmcnt(8)
	s_waitcnt lgkmcnt(0)
	s_setprio 1
	s_barrier
	v_mfma_f32_16x16x32_bf16 v[66:69], v[142:145], v[182:185], v[66:69]
	v_mfma_f32_16x16x32_bf16 v[66:69], v[146:149], v[186:189], v[66:69]
	v_mfma_f32_16x16x32_bf16 v[62:65], v[150:153], v[182:185], v[62:65]
	v_mfma_f32_16x16x32_bf16 v[62:65], v[154:157], v[186:189], v[62:65]
	v_mfma_f32_16x16x32_bf16 v[50:53], v[142:145], v[190:193], v[50:53]
	v_mfma_f32_16x16x32_bf16 v[50:53], v[146:149], v[194:197], v[50:53]
	v_mfma_f32_16x16x32_bf16 v[46:49], v[150:153], v[190:193], v[46:49]
	v_mfma_f32_16x16x32_bf16 v[46:49], v[154:157], v[194:197], v[46:49]
	v_mfma_f32_16x16x32_bf16 v[34:37], v[142:145], v[198:201], v[34:37]
	v_mfma_f32_16x16x32_bf16 v[34:37], v[146:149], v[202:205], v[34:37]
	v_mfma_f32_16x16x32_bf16 v[30:33], v[150:153], v[198:201], v[30:33]
	v_mfma_f32_16x16x32_bf16 v[30:33], v[154:157], v[202:205], v[30:33]
	v_mfma_f32_16x16x32_bf16 v[18:21], v[142:145], v[206:209], v[18:21]
	v_mfma_f32_16x16x32_bf16 v[18:21], v[146:149], v[210:213], v[18:21]
	v_mfma_f32_16x16x32_bf16 v[10:13], v[150:153], v[206:209], v[10:13]
	v_mfma_f32_16x16x32_bf16 v[10:13], v[154:157], v[210:213], v[10:13]
	v_mfma_f32_16x16x32_bf16 v[58:61], v[158:161], v[182:185], v[58:61]
	v_mfma_f32_16x16x32_bf16 v[58:61], v[162:165], v[186:189], v[58:61]
	v_mfma_f32_16x16x32_bf16 v[54:57], v[166:169], v[182:185], v[54:57]
	v_mfma_f32_16x16x32_bf16 v[54:57], v[170:173], v[186:189], v[54:57]
	v_mfma_f32_16x16x32_bf16 v[42:45], v[158:161], v[190:193], v[42:45]
	v_mfma_f32_16x16x32_bf16 v[42:45], v[162:165], v[194:197], v[42:45]
	v_mfma_f32_16x16x32_bf16 v[38:41], v[166:169], v[190:193], v[38:41]
	v_mfma_f32_16x16x32_bf16 v[38:41], v[170:173], v[194:197], v[38:41]
	v_mfma_f32_16x16x32_bf16 v[26:29], v[158:161], v[198:201], v[26:29]
	v_mfma_f32_16x16x32_bf16 v[26:29], v[162:165], v[202:205], v[26:29]
	v_mfma_f32_16x16x32_bf16 v[22:25], v[166:169], v[198:201], v[22:25]
	v_mfma_f32_16x16x32_bf16 v[22:25], v[170:173], v[202:205], v[22:25]
	v_mfma_f32_16x16x32_bf16 v[6:9], v[158:161], v[206:209], v[6:9]
	v_mfma_f32_16x16x32_bf16 v[6:9], v[162:165], v[210:213], v[6:9]
	v_mfma_f32_16x16x32_bf16 v[2:5], v[166:169], v[206:209], v[2:5]
	v_mfma_f32_16x16x32_bf16 v[2:5], v[170:173], v[210:213], v[2:5]
	s_barrier
	s_setprio 0
	s_add_u32 s22, s22, 0x100
	s_addc_u32 s23, s23, 0
	s_add_u32 s45, s45, 0x100
	s_addc_u32 s46, s46, 0
	s_cmp_ge_u32 s47, s39
	s_mov_b32 s24, s47
	s_cbranch_scc1 .Lpeel_exit_2

.Lpl3_join_1:
	s_waitcnt lgkmcnt(0)
	s_setprio 1
	s_barrier
	v_mfma_f32_16x16x32_bf16 v[130:133], v[134:137], v[194:197], 0
	v_mfma_f32_16x16x32_bf16 v[130:133], v[148:151], v[198:201], v[130:133]
	v_mfma_f32_16x16x32_bf16 v[122:125], v[152:155], v[194:197], 0
	v_mfma_f32_16x16x32_bf16 v[122:125], v[156:159], v[198:201], v[122:125]
	v_mfma_f32_16x16x32_bf16 v[114:117], v[134:137], v[202:205], 0
	v_mfma_f32_16x16x32_bf16 v[114:117], v[148:151], v[206:209], v[114:117]
	v_mfma_f32_16x16x32_bf16 v[106:109], v[152:155], v[202:205], 0
	v_mfma_f32_16x16x32_bf16 v[106:109], v[156:159], v[206:209], v[106:109]
	v_mfma_f32_16x16x32_bf16 v[98:101], v[134:137], v[210:213], 0
	v_mfma_f32_16x16x32_bf16 v[98:101], v[148:151], v[214:217], v[98:101]
	v_mfma_f32_16x16x32_bf16 v[90:93], v[152:155], v[210:213], 0
	v_mfma_f32_16x16x32_bf16 v[90:93], v[156:159], v[214:217], v[90:93]
	v_mfma_f32_16x16x32_bf16 v[82:85], v[134:137], v[218:221], 0
	v_mfma_f32_16x16x32_bf16 v[82:85], v[148:151], v[222:225], v[82:85]
	v_mfma_f32_16x16x32_bf16 v[74:77], v[152:155], v[218:221], 0
	v_mfma_f32_16x16x32_bf16 v[74:77], v[156:159], v[222:225], v[74:77]
	v_mfma_f32_16x16x32_bf16 v[126:129], v[160:163], v[194:197], 0
	v_mfma_f32_16x16x32_bf16 v[126:129], v[182:185], v[198:201], v[126:129]
	v_mfma_f32_16x16x32_bf16 v[118:121], v[186:189], v[194:197], 0
	v_mfma_f32_16x16x32_bf16 v[118:121], v[190:193], v[198:201], v[118:121]
	v_mfma_f32_16x16x32_bf16 v[110:113], v[160:163], v[202:205], 0
	v_mfma_f32_16x16x32_bf16 v[110:113], v[182:185], v[206:209], v[110:113]
	v_mfma_f32_16x16x32_bf16 v[102:105], v[186:189], v[202:205], 0
	v_mfma_f32_16x16x32_bf16 v[102:105], v[190:193], v[206:209], v[102:105]
	v_mfma_f32_16x16x32_bf16 v[94:97], v[160:163], v[210:213], 0
	v_mfma_f32_16x16x32_bf16 v[94:97], v[182:185], v[214:217], v[94:97]
	v_mfma_f32_16x16x32_bf16 v[86:89], v[186:189], v[210:213], 0
	v_mfma_f32_16x16x32_bf16 v[86:89], v[190:193], v[214:217], v[86:89]
	v_mfma_f32_16x16x32_bf16 v[78:81], v[160:163], v[218:221], 0
	v_mfma_f32_16x16x32_bf16 v[78:81], v[182:185], v[222:225], v[78:81]
	v_mfma_f32_16x16x32_bf16 v[70:73], v[186:189], v[218:221], 0
	v_mfma_f32_16x16x32_bf16 v[70:73], v[190:193], v[222:225], v[70:73]
	s_barrier
	s_setprio 0
	s_add_i32 s41, s41, s13
	v_lshl_add_u64 v[226:227], s[20:21], 0, v[0:1]
	s_mov_b32 m0, s41
	ds_read_b128 v[194:197], v175 offset:16384
	ds_read_b128 v[198:201], v175 offset:17408
	ds_read_b128 v[202:205], v175 offset:18432
	ds_read_b128 v[206:209], v175 offset:19456
	ds_read_b128 v[210:213], v175 offset:20480
	ds_read_b128 v[214:217], v175 offset:21504
	ds_read_b128 v[218:221], v175 offset:22528
	ds_read_b128 v[222:225], v175 offset:23552
	global_load_lds_dwordx4 v[226:227], off
	s_add_i32 m0, s41, 0x2000
	s_add_u32 s42, s20, 0x40000
	v_lshl_add_u64 v[228:229], s[20:21], 0, v[14:15]
	s_addc_u32 s43, s21, 0
	s_add_i32 s41, s44, s13
	global_load_lds_dwordx4 v[228:229], off
	v_lshl_add_u64 v[230:231], s[42:43], 0, v[0:1]
	s_mov_b32 m0, s41
	v_lshl_add_u64 v[232:233], s[22:23], 0, v[138:139]
	global_load_lds_dwordx4 v[230:231], off
	v_lshl_add_u64 v[230:231], s[42:43], 0, v[14:15]
	s_add_i32 m0, s41, 0x2000
	s_nop 0
	global_load_lds_dwordx4 v[230:231], off
	v_lshl_add_u64 v[230:231], s[22:23], 0, v[140:141]
	s_mov_b32 m0, s26
	s_nop 0
	global_load_lds_dwordx4 v[230:231], off
	s_mov_b32 m0, s27
	s_nop 0
	global_load_lds_dwordx4 v[232:233], off
	s_cmp_lg_u32 s2, 0
	s_cbranch_scc1 .Lpl3_relax_2
	s_waitcnt vmcnt(8)
	s_branch .Lpl3_join_2

.LBB0_893:
	s_add_u32 s20, s4, 0xfffc0080
	s_addc_u32 s21, s5, -1
	s_add_i32 s41, 0, 0x10000
	s_cmp_eq_u32 s40, 12
	s_cselect_b32 s23, s15, s21
	s_cselect_b32 s22, s36, s20
	s_cselect_b32 s21, s11, s39
	s_cselect_b32 s20, s37, s38
	s_add_i32 s44, 0, 0x14000
	v_add_u32_e32 v156, s41, v171
	v_add_u32_e32 v164, s44, v171
	ds_read_b128 v[134:137], v156
	ds_read_b128 v[148:151], v156 offset:1024
	ds_read_b128 v[152:155], v156 offset:2048
	ds_read_b128 v[156:159], v156 offset:3072
	ds_read_b128 v[160:163], v164
	ds_read_b128 v[182:185], v164 offset:1024
	ds_read_b128 v[186:189], v164 offset:2048
	ds_read_b128 v[190:193], v164 offset:3072
	v_lshl_add_u64 v[226:227], s[4:5], 0, v[144:145]
	s_add_i32 m0, s26, 0xc000
	ds_read_b128 v[194:197], v175
	ds_read_b128 v[198:201], v175 offset:1024
	ds_read_b128 v[202:205], v175 offset:2048
	ds_read_b128 v[206:209], v175 offset:3072
	ds_read_b128 v[210:213], v175 offset:4096
	ds_read_b128 v[214:217], v175 offset:5120
	ds_read_b128 v[218:221], v175 offset:6144
	ds_read_b128 v[222:225], v175 offset:7168
	global_load_lds_dwordx4 v[226:227], off
	v_lshl_add_u64 v[226:227], s[4:5], 0, v[146:147]
	s_add_i32 m0, s26, 0xe000
	s_nop 0
	global_load_lds_dwordx4 v[226:227], off
	s_waitcnt vmcnt(8)
	s_waitcnt lgkmcnt(0)
	s_setprio 1
	s_barrier
	v_mfma_f32_16x16x32_bf16 v[130:133], v[134:137], v[194:197], v[130:133]
	v_mfma_f32_16x16x32_bf16 v[130:133], v[148:151], v[198:201], v[130:133]
	v_mfma_f32_16x16x32_bf16 v[122:125], v[152:155], v[194:197], v[122:125]
	v_mfma_f32_16x16x32_bf16 v[122:125], v[156:159], v[198:201], v[122:125]
	v_mfma_f32_16x16x32_bf16 v[114:117], v[134:137], v[202:205], v[114:117]
	v_mfma_f32_16x16x32_bf16 v[114:117], v[148:151], v[206:209], v[114:117]
	v_mfma_f32_16x16x32_bf16 v[106:109], v[152:155], v[202:205], v[106:109]
	v_mfma_f32_16x16x32_bf16 v[106:109], v[156:159], v[206:209], v[106:109]
	v_mfma_f32_16x16x32_bf16 v[98:101], v[134:137], v[210:213], v[98:101]
	v_mfma_f32_16x16x32_bf16 v[98:101], v[148:151], v[214:217], v[98:101]
	v_mfma_f32_16x16x32_bf16 v[90:93], v[152:155], v[210:213], v[90:93]
	v_mfma_f32_16x16x32_bf16 v[90:93], v[156:159], v[214:217], v[90:93]
	v_mfma_f32_16x16x32_bf16 v[82:85], v[134:137], v[218:221], v[82:85]
	v_mfma_f32_16x16x32_bf16 v[82:85], v[148:151], v[222:225], v[82:85]
	v_mfma_f32_16x16x32_bf16 v[74:77], v[152:155], v[218:221], v[74:77]
	v_mfma_f32_16x16x32_bf16 v[74:77], v[156:159], v[222:225], v[74:77]
	v_mfma_f32_16x16x32_bf16 v[126:129], v[160:163], v[194:197], v[126:129]
	v_mfma_f32_16x16x32_bf16 v[126:129], v[182:185], v[198:201], v[126:129]
	v_mfma_f32_16x16x32_bf16 v[118:121], v[186:189], v[194:197], v[118:121]
	v_mfma_f32_16x16x32_bf16 v[118:121], v[190:193], v[198:201], v[118:121]
	v_mfma_f32_16x16x32_bf16 v[110:113], v[160:163], v[202:205], v[110:113]
	v_mfma_f32_16x16x32_bf16 v[110:113], v[182:185], v[206:209], v[110:113]
	v_mfma_f32_16x16x32_bf16 v[102:105], v[186:189], v[202:205], v[102:105]
	v_mfma_f32_16x16x32_bf16 v[102:105], v[190:193], v[206:209], v[102:105]
	v_mfma_f32_16x16x32_bf16 v[94:97], v[160:163], v[210:213], v[94:97]
	v_mfma_f32_16x16x32_bf16 v[94:97], v[182:185], v[214:217], v[94:97]
	v_mfma_f32_16x16x32_bf16 v[86:89], v[186:189], v[210:213], v[86:89]
	v_mfma_f32_16x16x32_bf16 v[86:89], v[190:193], v[214:217], v[86:89]
	v_mfma_f32_16x16x32_bf16 v[78:81], v[160:163], v[218:221], v[78:81]
	v_mfma_f32_16x16x32_bf16 v[78:81], v[182:185], v[222:225], v[78:81]
	v_mfma_f32_16x16x32_bf16 v[70:73], v[186:189], v[218:221], v[70:73]
	v_mfma_f32_16x16x32_bf16 v[70:73], v[190:193], v[222:225], v[70:73]
	s_barrier
	s_setprio 0
	s_add_i32 s41, s41, s13
	v_lshl_add_u64 v[226:227], s[20:21], 0, v[0:1]
	s_mov_b32 m0, s41
	ds_read_b128 v[194:197], v175 offset:16384
	ds_read_b128 v[198:201], v175 offset:17408
	ds_read_b128 v[202:205], v175 offset:18432
	ds_read_b128 v[206:209], v175 offset:19456
	ds_read_b128 v[210:213], v175 offset:20480
	ds_read_b128 v[214:217], v175 offset:21504
	ds_read_b128 v[218:221], v175 offset:22528
	ds_read_b128 v[222:225], v175 offset:23552
	global_load_lds_dwordx4 v[226:227], off
	s_add_i32 m0, s41, 0x2000
	s_add_u32 s42, s20, 0x40000
	v_lshl_add_u64 v[228:229], s[20:21], 0, v[14:15]
	s_addc_u32 s43, s21, 0
	s_add_i32 s41, s44, s13
	global_load_lds_dwordx4 v[228:229], off
	v_lshl_add_u64 v[230:231], s[42:43], 0, v[0:1]
	s_mov_b32 m0, s41
	v_lshl_add_u64 v[232:233], s[22:23], 0, v[138:139]
	global_load_lds_dwordx4 v[230:231], off
	v_lshl_add_u64 v[230:231], s[42:43], 0, v[14:15]
	s_add_i32 m0, s41, 0x2000
	s_nop 0
	global_load_lds_dwordx4 v[230:231], off
	v_lshl_add_u64 v[230:231], s[22:23], 0, v[140:141]
	s_mov_b32 m0, s26
	s_nop 0
	global_load_lds_dwordx4 v[230:231], off
	s_mov_b32 m0, s27
	s_nop 0
	global_load_lds_dwordx4 v[232:233], off
	s_waitcnt vmcnt(8)
	s_waitcnt lgkmcnt(0)
	s_setprio 1
	s_barrier
	v_mfma_f32_16x16x32_bf16 v[66:69], v[134:137], v[194:197], v[66:69]
	v_mfma_f32_16x16x32_bf16 v[66:69], v[148:151], v[198:201], v[66:69]
	v_mfma_f32_16x16x32_bf16 v[58:61], v[152:155], v[194:197], v[58:61]
	v_mfma_f32_16x16x32_bf16 v[58:61], v[156:159], v[198:201], v[58:61]
	v_mfma_f32_16x16x32_bf16 v[50:53], v[134:137], v[202:205], v[50:53]
	v_mfma_f32_16x16x32_bf16 v[50:53], v[148:151], v[206:209], v[50:53]
	v_mfma_f32_16x16x32_bf16 v[42:45], v[152:155], v[202:205], v[42:45]
	v_mfma_f32_16x16x32_bf16 v[42:45], v[156:159], v[206:209], v[42:45]
	v_mfma_f32_16x16x32_bf16 v[34:37], v[134:137], v[210:213], v[34:37]
	v_mfma_f32_16x16x32_bf16 v[34:37], v[148:151], v[214:217], v[34:37]
	v_mfma_f32_16x16x32_bf16 v[26:29], v[152:155], v[210:213], v[26:29]
	v_mfma_f32_16x16x32_bf16 v[26:29], v[156:159], v[214:217], v[26:29]
	v_mfma_f32_16x16x32_bf16 v[18:21], v[134:137], v[218:221], v[18:21]
	v_mfma_f32_16x16x32_bf16 v[18:21], v[148:151], v[222:225], v[18:21]
	v_mfma_f32_16x16x32_bf16 v[6:9], v[152:155], v[218:221], v[6:9]
	v_mfma_f32_16x16x32_bf16 v[6:9], v[156:159], v[222:225], v[6:9]
	v_mfma_f32_16x16x32_bf16 v[62:65], v[160:163], v[194:197], v[62:65]
	v_mfma_f32_16x16x32_bf16 v[62:65], v[182:185], v[198:201], v[62:65]
	v_mfma_f32_16x16x32_bf16 v[54:57], v[186:189], v[194:197], v[54:57]
	v_mfma_f32_16x16x32_bf16 v[54:57], v[190:193], v[198:201], v[54:57]
	v_mfma_f32_16x16x32_bf16 v[46:49], v[160:163], v[202:205], v[46:49]
	v_mfma_f32_16x16x32_bf16 v[46:49], v[182:185], v[206:209], v[46:49]
	v_mfma_f32_16x16x32_bf16 v[38:41], v[186:189], v[202:205], v[38:41]
	v_mfma_f32_16x16x32_bf16 v[38:41], v[190:193], v[206:209], v[38:41]
	v_mfma_f32_16x16x32_bf16 v[30:33], v[160:163], v[210:213], v[30:33]
	v_mfma_f32_16x16x32_bf16 v[30:33], v[182:185], v[214:217], v[30:33]
	v_mfma_f32_16x16x32_bf16 v[22:25], v[186:189], v[210:213], v[22:25]
	v_mfma_f32_16x16x32_bf16 v[22:25], v[190:193], v[214:217], v[22:25]
	v_mfma_f32_16x16x32_bf16 v[10:13], v[160:163], v[218:221], v[10:13]
	v_mfma_f32_16x16x32_bf16 v[10:13], v[182:185], v[222:225], v[10:13]
	v_mfma_f32_16x16x32_bf16 v[2:5], v[186:189], v[218:221], v[2:5]
	v_mfma_f32_16x16x32_bf16 v[2:5], v[190:193], v[222:225], v[2:5]
	s_barrier
	s_setprio 0
	s_add_i32 s41, 0, 0x18000
	s_add_i32 s42, 0, 0x1c000
	v_add_u32_e32 v156, s41, v171
	v_add_u32_e32 v164, s42, v171
	ds_read_b128 v[134:137], v156
	ds_read_b128 v[148:151], v156 offset:1024
	ds_read_b128 v[152:155], v156 offset:2048
	ds_read_b128 v[156:159], v156 offset:3072
	ds_read_b128 v[160:163], v164
	ds_read_b128 v[182:185], v164 offset:1024
	ds_read_b128 v[186:189], v164 offset:2048
	ds_read_b128 v[190:193], v164 offset:3072
	s_add_u32 s22, s22, 0x40000
	s_addc_u32 s23, s23, 0
	s_mov_b32 m0, s28
	v_lshl_add_u64 v[234:235], s[22:23], 0, v[140:141]
	ds_read_b128 v[194:197], v175 offset:32768
	ds_read_b128 v[198:201], v175 offset:33792
	ds_read_b128 v[202:205], v175 offset:34816
	ds_read_b128 v[206:209], v175 offset:35840
	ds_read_b128 v[210:213], v175 offset:36864
	ds_read_b128 v[214:217], v175 offset:37888
	ds_read_b128 v[218:221], v175 offset:38912
	ds_read_b128 v[222:225], v175 offset:39936
	global_load_lds_dwordx4 v[234:235], off
	v_lshl_add_u64 v[234:235], s[22:23], 0, v[138:139]
	s_mov_b32 m0, s29
	s_nop 0
	global_load_lds_dwordx4 v[234:235], off
	s_waitcnt vmcnt(8)
	s_waitcnt lgkmcnt(0)
	s_setprio 1
	s_barrier
	v_mfma_f32_16x16x32_bf16 v[130:133], v[134:137], v[194:197], v[130:133]
	v_mfma_f32_16x16x32_bf16 v[130:133], v[148:151], v[198:201], v[130:133]
	v_mfma_f32_16x16x32_bf16 v[122:125], v[152:155], v[194:197], v[122:125]
	v_mfma_f32_16x16x32_bf16 v[122:125], v[156:159], v[198:201], v[122:125]
	v_mfma_f32_16x16x32_bf16 v[114:117], v[134:137], v[202:205], v[114:117]
	v_mfma_f32_16x16x32_bf16 v[114:117], v[148:151], v[206:209], v[114:117]
	v_mfma_f32_16x16x32_bf16 v[106:109], v[152:155], v[202:205], v[106:109]
	v_mfma_f32_16x16x32_bf16 v[106:109], v[156:159], v[206:209], v[106:109]
	v_mfma_f32_16x16x32_bf16 v[98:101], v[134:137], v[210:213], v[98:101]
	v_mfma_f32_16x16x32_bf16 v[98:101], v[148:151], v[214:217], v[98:101]
	v_mfma_f32_16x16x32_bf16 v[90:93], v[152:155], v[210:213], v[90:93]
	v_mfma_f32_16x16x32_bf16 v[90:93], v[156:159], v[214:217], v[90:93]
	v_mfma_f32_16x16x32_bf16 v[82:85], v[134:137], v[218:221], v[82:85]
	v_mfma_f32_16x16x32_bf16 v[82:85], v[148:151], v[222:225], v[82:85]
	v_mfma_f32_16x16x32_bf16 v[74:77], v[152:155], v[218:221], v[74:77]
	v_mfma_f32_16x16x32_bf16 v[74:77], v[156:159], v[222:225], v[74:77]
	v_mfma_f32_16x16x32_bf16 v[126:129], v[160:163], v[194:197], v[126:129]
	v_mfma_f32_16x16x32_bf16 v[126:129], v[182:185], v[198:201], v[126:129]
	v_mfma_f32_16x16x32_bf16 v[118:121], v[186:189], v[194:197], v[118:121]
	v_mfma_f32_16x16x32_bf16 v[118:121], v[190:193], v[198:201], v[118:121]
	v_mfma_f32_16x16x32_bf16 v[110:113], v[160:163], v[202:205], v[110:113]
	v_mfma_f32_16x16x32_bf16 v[110:113], v[182:185], v[206:209], v[110:113]
	v_mfma_f32_16x16x32_bf16 v[102:105], v[186:189], v[202:205], v[102:105]
	v_mfma_f32_16x16x32_bf16 v[102:105], v[190:193], v[206:209], v[102:105]
	v_mfma_f32_16x16x32_bf16 v[94:97], v[160:163], v[210:213], v[94:97]
	v_mfma_f32_16x16x32_bf16 v[94:97], v[182:185], v[214:217], v[94:97]
	v_mfma_f32_16x16x32_bf16 v[86:89], v[186:189], v[210:213], v[86:89]
	v_mfma_f32_16x16x32_bf16 v[86:89], v[190:193], v[214:217], v[86:89]
	v_mfma_f32_16x16x32_bf16 v[78:81], v[160:163], v[218:221], v[78:81]
	v_mfma_f32_16x16x32_bf16 v[78:81], v[182:185], v[222:225], v[78:81]
	v_mfma_f32_16x16x32_bf16 v[70:73], v[186:189], v[218:221], v[70:73]
	v_mfma_f32_16x16x32_bf16 v[70:73], v[190:193], v[222:225], v[70:73]
	s_barrier
	s_setprio 0
	s_add_i32 s22, s41, s13
	v_lshl_add_u64 v[226:227], v[226:227], 0, s[92:93]
	s_mov_b32 m0, s22
	ds_read_b128 v[194:197], v175 offset:49152
	ds_read_b128 v[198:201], v175 offset:50176
	ds_read_b128 v[202:205], v175 offset:51200
	ds_read_b128 v[206:209], v175 offset:52224
	ds_read_b128 v[210:213], v175 offset:53248
	ds_read_b128 v[214:217], v175 offset:54272
	ds_read_b128 v[218:221], v175 offset:55296
	ds_read_b128 v[222:225], v175 offset:56320
	global_load_lds_dwordx4 v[226:227], off
	s_add_i32 m0, s22, 0x2000
	s_add_u32 s20, s20, 0x40080
	v_lshl_add_u64 v[226:227], v[228:229], 0, s[92:93]
	s_addc_u32 s21, s21, 0
	s_add_i32 s22, s42, s13
	global_load_lds_dwordx4 v[226:227], off
	v_lshl_add_u64 v[226:227], s[20:21], 0, v[0:1]
	s_mov_b32 m0, s22
	s_nop 0
	global_load_lds_dwordx4 v[226:227], off
	v_lshl_add_u64 v[226:227], s[20:21], 0, v[14:15]
	s_add_i32 m0, s22, 0x2000
	s_nop 0
	global_load_lds_dwordx4 v[226:227], off
	v_lshl_add_u64 v[226:227], v[230:231], 0, s[92:93]
	s_mov_b32 m0, s30
	s_nop 0
	global_load_lds_dwordx4 v[226:227], off
	v_lshl_add_u64 v[226:227], v[232:233], 0, s[92:93]
	s_mov_b32 m0, s31
	s_nop 0
	global_load_lds_dwordx4 v[226:227], off
	s_waitcnt vmcnt(8)
	s_waitcnt lgkmcnt(0)
	s_setprio 1
	s_barrier
	v_mfma_f32_16x16x32_bf16 v[66:69], v[134:137], v[194:197], v[66:69]
	v_mfma_f32_16x16x32_bf16 v[66:69], v[148:151], v[198:201], v[66:69]
	v_mfma_f32_16x16x32_bf16 v[58:61], v[152:155], v[194:197], v[58:61]
	v_mfma_f32_16x16x32_bf16 v[58:61], v[156:159], v[198:201], v[58:61]
	v_mfma_f32_16x16x32_bf16 v[50:53], v[134:137], v[202:205], v[50:53]
	v_mfma_f32_16x16x32_bf16 v[50:53], v[148:151], v[206:209], v[50:53]
	v_mfma_f32_16x16x32_bf16 v[42:45], v[152:155], v[202:205], v[42:45]
	v_mfma_f32_16x16x32_bf16 v[42:45], v[156:159], v[206:209], v[42:45]
	v_mfma_f32_16x16x32_bf16 v[34:37], v[134:137], v[210:213], v[34:37]
	v_mfma_f32_16x16x32_bf16 v[34:37], v[148:151], v[214:217], v[34:37]
	v_mfma_f32_16x16x32_bf16 v[26:29], v[152:155], v[210:213], v[26:29]
	v_mfma_f32_16x16x32_bf16 v[26:29], v[156:159], v[214:217], v[26:29]
	v_mfma_f32_16x16x32_bf16 v[18:21], v[134:137], v[218:221], v[18:21]
	v_mfma_f32_16x16x32_bf16 v[18:21], v[148:151], v[222:225], v[18:21]
	v_mfma_f32_16x16x32_bf16 v[6:9], v[152:155], v[218:221], v[6:9]
	v_mfma_f32_16x16x32_bf16 v[6:9], v[156:159], v[222:225], v[6:9]
	v_mfma_f32_16x16x32_bf16 v[62:65], v[160:163], v[194:197], v[62:65]
	v_mfma_f32_16x16x32_bf16 v[62:65], v[182:185], v[198:201], v[62:65]
	v_mfma_f32_16x16x32_bf16 v[54:57], v[186:189], v[194:197], v[54:57]
	v_mfma_f32_16x16x32_bf16 v[54:57], v[190:193], v[198:201], v[54:57]
	v_mfma_f32_16x16x32_bf16 v[46:49], v[160:163], v[202:205], v[46:49]
	v_mfma_f32_16x16x32_bf16 v[46:49], v[182:185], v[206:209], v[46:49]
	v_mfma_f32_16x16x32_bf16 v[38:41], v[186:189], v[202:205], v[38:41]
	v_mfma_f32_16x16x32_bf16 v[38:41], v[190:193], v[206:209], v[38:41]
	v_mfma_f32_16x16x32_bf16 v[30:33], v[160:163], v[210:213], v[30:33]
	v_mfma_f32_16x16x32_bf16 v[30:33], v[182:185], v[214:217], v[30:33]
	v_mfma_f32_16x16x32_bf16 v[22:25], v[186:189], v[210:213], v[22:25]
	v_mfma_f32_16x16x32_bf16 v[22:25], v[190:193], v[214:217], v[22:25]
	v_mfma_f32_16x16x32_bf16 v[10:13], v[160:163], v[218:221], v[10:13]
	v_mfma_f32_16x16x32_bf16 v[10:13], v[182:185], v[222:225], v[10:13]
	v_mfma_f32_16x16x32_bf16 v[2:5], v[186:189], v[218:221], v[2:5]
	v_mfma_f32_16x16x32_bf16 v[2:5], v[190:193], v[222:225], v[2:5]
	s_barrier
	s_setprio 0
	s_add_i32 s40, s40, 2
	s_add_u32 s4, s4, 0x100
	s_addc_u32 s5, s5, 0
	s_add_u32 s38, s38, 0x100
	s_addc_u32 s39, s39, 0
	s_cmp_gt_u32 s40, 13
	s_cbranch_scc0 .LBB0_893
